# gMLP unit epilogue (layer 1): same hoisting of the serialized u/bias loads, in two register batches
# speedup vs baseline: 1.0160x; 1.0160x over previous
; __device__ __forceinline__ unsigned cvt_pk_bf16(float lo, float hi) { unsigned r; asm volatile("v_cvt_pk_bf16_f32 %0, %1, %2" : "=v"(r) : "v"(lo), "v"(hi)); return r; }
;     __device__ __forceinline__ bf16_t* bfp(size_t off) const { return (bf16_t*)(ws + off); }
; __device__ void gmlp_unit(const Ctx& c, int tid, int l, int ch, int g, unsigned short* T) {
;     const KParams pk = c.p;
;     const int lane = tid & 63, wave = tid >> 6;
;     const int r32 = lane & 31, hi = lane >> 5, pblk = wave >> 1, cb0 = (wave & 1) * 2;
;     const float* wsr = pk->in[10] + ((size_t)(l * 8 + g) * 128 + pblk * 32 + r32) * 128 + hi * 8;
;     const bf16_t* vn = c.bfp(WS_VN) + (size_t)(ch * 128) * 1024 + g * 128;
;     bf16_t* AM0 = c.bfp(WS_AM);
;     {
;         const int q = tid >> 4, c8 = (tid & 15) * 8;
;         u32x4 v[4];
; #pragma unroll
;         for (int ps = 0; ps < 4; ++ps) v[ps] = *(const u32x4*)(vn + (size_t)(q + 32 * ps) * 1024 + c8);
; #pragma unroll
;         for (int ps = 0; ps < 4; ++ps) { unsigned short* d = T + (q + 32 * ps) * 132 + c8; *(u32x2*)d = (u32x2){v[ps].x, v[ps].y}; *(u32x2*)(d + 4) = (u32x2){v[ps].z, v[ps].w}; }
;     }
;     bf16x8 af[8];
; #pragma unroll
;     for (int ks = 0; ks < 8; ++ks) { const f32x4 a0 = *(const f32x4*)(wsr + ks * 16), a1 = *(const f32x4*)(wsr + ks * 16 + 4);
;         u32x4 aw; aw.x = cvt_pk_bf16(a0[0], a0[1]); aw.y = cvt_pk_bf16(a0[2], a0[3]); aw.z = cvt_pk_bf16(a1[0], a1[1]); aw.w = cvt_pk_bf16(a1[2], a1[3]);
;         af[ks] = *reinterpret_cast<const bf16x8*>(&aw); }
;     __syncthreads();
;     f32x16 acc0 = {}, acc1 = {};
;     const unsigned short* tb = T + (hi * 8) * 132 + cb0 * 32 + r32;
; #pragma unroll
;     for (int ks = 0; ks < 8; ++ks) {
;         bf16x8 b0, b1;
; #pragma unroll
;         for (int j = 0; j < 8; ++j) { b0[j] = (short)tb[(ks * 16 + j) * 132]; b1[j] = (short)tb[(ks * 16 + j) * 132 + 32]; }
.LBB0_1544:
	s_ashr_i32 s6, s35, 3
	s_lshl_b32 s16, s6, 7
	s_and_b32 s7, s10, 0x380
	s_ashr_i32 s17, s16, 31
	s_or_b32 s4, s7, 0x400
	s_lshl_b64 s[16:17], s[16:17], 11
	s_add_u32 s15, s8, s16
	s_addc_u32 s17, s9, s17
	s_lshl_b32 s18, s7, 1
	s_add_u32 s16, s15, s18
	v_lshl_add_u64 v[0:1], v[32:33], 0, s[4:5]
	s_addc_u32 s17, s17, 0
	v_lshlrev_b64 v[0:1], 9, v[0:1]
	v_lshl_add_u64 v[8:9], s[16:17], 0, v[34:35]
	v_lshl_add_u64 v[24:25], v[108:109], 0, v[0:1]
	v_lshl_add_u64 v[26:27], v[8:9], 0, v[36:37]
	global_load_dwordx4 v[0:3], v[24:25], off offset:16
	global_load_dwordx4 v[4:7], v[24:25], off
	v_lshl_add_u64 v[28:29], v[8:9], 0, v[38:39]
	v_lshl_add_u64 v[30:31], v[8:9], 0, v[40:41]
	v_lshl_add_u64 v[114:115], v[8:9], 0, v[42:43]
	global_load_dwordx4 v[8:11], v[26:27], off
	global_load_dwordx4 v[12:15], v[28:29], off
	global_load_dwordx4 v[16:19], v[30:31], off
	global_load_dwordx4 v[20:23], v[114:115], off
	v_add_u32_e32 v49, 0x2100, v45
	v_add_u32_e32 v53, 0x4200, v45
	v_add_u32_e32 v57, 0x6300, v45
	s_ashr_i32 s7, s6, 31
	s_lshl_b64 s[6:7], s[6:7], 18
	s_add_u32 s6, s50, s6
	s_addc_u32 s7, s51, s7
	s_add_u32 s6, s6, s18
	v_mov_b32_e32 v111, v35
	s_addc_u32 s7, s7, 0
	v_mov_b32_e32 v113, v35
	v_lshl_add_u64 v[26:27], s[6:7], 0, v[110:111]
	v_lshl_add_u64 v[114:115], v[26:27], 0, v[112:113]
	v_add_u32_e32 v118, s4, v44
	v_ashrrev_i32_e32 v119, 31, v118
	v_lshl_add_u64 v[116:117], v[114:115], 0, v[46:47]
	s_add_i32 s35, s35, s38
	s_add_i32 s10, s10, s11
	s_cmpk_lt_i32 s35, 0x200
	s_waitcnt vmcnt(0)
	ds_write2_b64 v45, v[8:9], v[10:11] offset1:1
	ds_write2_b64 v49, v[12:13], v[14:15] offset1:1
	ds_write2_b64 v53, v[16:17], v[18:19] offset1:1
	ds_write2_b64 v57, v[20:21], v[22:23] offset1:1
	v_cvt_pk_bf16_f32 v4, v4, v5
	v_cvt_pk_bf16_f32 v5, v6, v7
	v_cvt_pk_bf16_f32 v6, v0, v1
	v_cvt_pk_bf16_f32 v7, v2, v3
	global_load_dwordx4 v[0:3], v[24:25], off offset:64
	global_load_dwordx4 v[8:11], v[24:25], off offset:80
	s_waitcnt vmcnt(1)
	v_cvt_pk_bf16_f32 v122, v0, v1
	v_cvt_pk_bf16_f32 v123, v2, v3
	s_waitcnt vmcnt(0)
	v_cvt_pk_bf16_f32 v124, v8, v9
	v_cvt_pk_bf16_f32 v125, v10, v11
	global_load_dwordx4 v[0:3], v[24:25], off offset:128
	global_load_dwordx4 v[8:11], v[24:25], off offset:144
	s_waitcnt vmcnt(1)
	v_cvt_pk_bf16_f32 v126, v0, v1
	v_cvt_pk_bf16_f32 v127, v2, v3
	s_waitcnt vmcnt(0)
	v_cvt_pk_bf16_f32 v128, v8, v9
	v_cvt_pk_bf16_f32 v129, v10, v11
	global_load_dwordx4 v[0:3], v[24:25], off offset:192
	global_load_dwordx4 v[8:11], v[24:25], off offset:208
	s_waitcnt vmcnt(1)
	v_cvt_pk_bf16_f32 v130, v0, v1
	v_cvt_pk_bf16_f32 v131, v2, v3
	s_waitcnt vmcnt(0)
	v_cvt_pk_bf16_f32 v132, v8, v9
	v_cvt_pk_bf16_f32 v133, v10, v11
	global_load_dwordx4 v[0:3], v[24:25], off offset:256
	global_load_dwordx4 v[8:11], v[24:25], off offset:272
	s_waitcnt vmcnt(1)
	v_cvt_pk_bf16_f32 v134, v0, v1
	v_cvt_pk_bf16_f32 v135, v2, v3
	s_waitcnt vmcnt(0)
	v_cvt_pk_bf16_f32 v136, v8, v9
	v_cvt_pk_bf16_f32 v137, v10, v11
	global_load_dwordx4 v[0:3], v[24:25], off offset:320
	global_load_dwordx4 v[8:11], v[24:25], off offset:336
	s_waitcnt vmcnt(1)
	v_cvt_pk_bf16_f32 v138, v0, v1
	v_cvt_pk_bf16_f32 v139, v2, v3
	s_waitcnt vmcnt(0)
	v_cvt_pk_bf16_f32 v140, v8, v9
	v_cvt_pk_bf16_f32 v141, v10, v11
	global_load_dwordx4 v[0:3], v[24:25], off offset:384
	global_load_dwordx4 v[8:11], v[24:25], off offset:400
	s_waitcnt vmcnt(1)
	v_cvt_pk_bf16_f32 v142, v0, v1
	v_cvt_pk_bf16_f32 v143, v2, v3
	s_waitcnt vmcnt(0)
	v_cvt_pk_bf16_f32 v144, v8, v9
	v_cvt_pk_bf16_f32 v145, v10, v11
	global_load_dwordx4 v[0:3], v[24:25], off offset:448
	global_load_dwordx4 v[8:11], v[24:25], off offset:464
	s_waitcnt vmcnt(1)
	v_cvt_pk_bf16_f32 v146, v0, v1
	v_cvt_pk_bf16_f32 v147, v2, v3
	s_waitcnt vmcnt(0)
	v_cvt_pk_bf16_f32 v148, v8, v9
	v_cvt_pk_bf16_f32 v149, v10, v11
	s_waitcnt lgkmcnt(0)
	s_barrier
	ds_read_u16 v0, v120
	ds_read_u16 v8, v120 offset:64
	ds_read_u16 v9, v120 offset:264
	ds_read_u16 v10, v120 offset:328
	ds_read_u16 v1, v120 offset:528
	ds_read_u16 v11, v120 offset:592
	ds_read_u16 v12, v120 offset:792
	ds_read_u16 v13, v120 offset:856
	ds_read_u16 v2, v120 offset:1056
	ds_read_u16 v14, v120 offset:1120
	ds_read_u16 v15, v120 offset:1320
	ds_read_u16 v49, v120 offset:1384
	ds_read_u16 v3, v120 offset:1584
	ds_read_u16 v53, v120 offset:1648
	ds_read_u16 v16, v120 offset:1848
	ds_read_u16 v57, v120 offset:1912
	ds_read_u16 v61, v120 offset:4224
	ds_read_u16 v65, v120 offset:4288
	ds_read_u16 v69, v120 offset:4488
	ds_read_u16 v73, v120 offset:4552
	ds_read_u16 v77, v120 offset:4752
	ds_read_u16 v81, v120 offset:4816
	ds_read_u16 v85, v120 offset:5016
	ds_read_u16 v89, v120 offset:5080
	ds_read_u16 v93, v120 offset:5280
	ds_read_u16 v97, v120 offset:5344
	ds_read_u16 v101, v120 offset:5544
	ds_read_u16 v105, v120 offset:5608
	ds_read_u16 v111, v120 offset:5808
	ds_read_u16 v113, v120 offset:5872
	ds_read_u16 v121, v120 offset:6072
	ds_read_u16 v154, v120 offset:6136
	ds_read_u16 v155, v120 offset:8448
	ds_read_u16 v156, v120 offset:8512
	ds_read_u16 v157, v120 offset:8712
	ds_read_u16 v158, v120 offset:8776
	ds_read_u16 v159, v120 offset:8976
	ds_read_u16 v160, v120 offset:9040
	ds_read_u16 v161, v120 offset:9240
	ds_read_u16 v162, v120 offset:9304
	ds_read_u16 v163, v120 offset:9504
	ds_read_u16 v164, v120 offset:9568
	ds_read_u16 v165, v120 offset:9768
	ds_read_u16 v166, v120 offset:9832
	ds_read_u16 v167, v120 offset:10032
	ds_read_u16 v168, v120 offset:10096
	ds_read_u16 v169, v120 offset:10296
	ds_read_u16 v170, v120 offset:10360
	ds_read_u16 v171, v120 offset:12672
	ds_read_u16 v172, v120 offset:12736
	ds_read_u16 v173, v120 offset:12936
	ds_read_u16 v174, v120 offset:13000
; __device__ __forceinline__ int crow(int r, int hi) { return (r & 3) + 8 * (r >> 2) + 4 * hi; }
; __device__ void gmlp_unit(const Ctx& c, int tid, int l, int ch, int g, unsigned short* T) {
;     ...
; #pragma unroll
;     for (int ks = 0; ks < 8; ++ks) {
;         bf16x8 b0, b1;
; #pragma unroll
;         for (int j = 0; j < 8; ++j) { b0[j] = (short)tb[(ks * 16 + j) * 132]; b1[j] = (short)tb[(ks * 16 + j) * 132 + 32]; }
;         acc0 = __builtin_amdgcn_mfma_f32_32x32x16_bf16(af[ks], b0, acc0, 0, 0, 0);
;         acc1 = __builtin_amdgcn_mfma_f32_32x32x16_bf16(af[ks], b1, acc1, 0, 0, 0); }
; #pragma unroll
;     for (int r = 0; r < 16; ++r) { const int prow = pblk * 32 + att::crow(r, hi); const size_t t = (size_t)ch * 128 + prow;
;         const float bias = pk->in[11][(l * 8 + g) * 128 + prow];
	ds_read_u16 v175, v120 offset:13200
	ds_read_u16 v176, v120 offset:13264
	ds_read_u16 v177, v120 offset:13464
	ds_read_u16 v178, v120 offset:13528
	ds_read_u16 v179, v120 offset:13728
	ds_read_u16 v180, v120 offset:13792
	ds_read_u16 v181, v120 offset:13992
	ds_read_u16 v182, v120 offset:14056
	ds_read_u16 v183, v120 offset:14256
	ds_read_u16 v184, v120 offset:14320
	ds_read_u16 v185, v120 offset:14520
	ds_read_u16 v186, v120 offset:14584
	ds_read_u16 v187, v120 offset:16896
	ds_read_u16 v188, v120 offset:16960
	ds_read_u16 v189, v120 offset:17160
	ds_read_u16 v190, v120 offset:17224
	ds_read_u16 v191, v120 offset:17424
	ds_read_u16 v192, v120 offset:17488
	ds_read_u16 v193, v120 offset:17688
	ds_read_u16 v194, v120 offset:17752
	ds_read_u16 v195, v120 offset:17952
	ds_read_u16 v196, v120 offset:18016
	ds_read_u16 v197, v120 offset:18216
	ds_read_u16 v198, v120 offset:18280
	ds_read_u16 v199, v120 offset:18480
	ds_read_u16 v200, v120 offset:18544
	ds_read_u16 v201, v120 offset:18744
	ds_read_u16 v202, v120 offset:18808
	ds_read_u16 v203, v120 offset:21120
	ds_read_u16 v204, v120 offset:21184
	ds_read_u16 v205, v120 offset:21384
	ds_read_u16 v206, v120 offset:21448
	ds_read_u16 v207, v120 offset:21648
	ds_read_u16 v208, v120 offset:21712
	ds_read_u16 v209, v120 offset:21912
	ds_read_u16 v210, v120 offset:21976
	ds_read_u16 v211, v120 offset:22176
	ds_read_u16 v212, v120 offset:22240
	ds_read_u16 v213, v120 offset:22440
	ds_read_u16 v214, v120 offset:22504
	ds_read_u16 v215, v120 offset:22704
	s_waitcnt lgkmcnt(14)
	v_perm_b32 v3, v16, v3, s14
	v_perm_b32 v2, v15, v2, s14
	v_perm_b32 v1, v12, v1, s14
	v_perm_b32 v0, v9, v0, s14
	v_perm_b32 v153, v121, v111, s14
	v_perm_b32 v152, v101, v93, s14
	v_mfma_f32_32x32x16_bf16 v[16:31], v[4:7], v[0:3], 0
	v_perm_b32 v3, v57, v53, s14
	v_perm_b32 v2, v49, v14, s14
	v_perm_b32 v1, v13, v11, s14
	v_perm_b32 v0, v10, v8, s14
	v_perm_b32 v151, v85, v77, s14
	v_perm_b32 v150, v69, v61, s14
	ds_read_u16 v218, v120 offset:22768
	ds_read_u16 v219, v120 offset:22968
	ds_read_u16 v220, v120 offset:23032
	v_mfma_f32_32x32x16_bf16 v[0:15], v[4:7], v[0:3], 0
	ds_read_u16 v49, v120 offset:25344
	ds_read_u16 v53, v120 offset:25408
	ds_read_u16 v57, v120 offset:25608
	ds_read_u16 v61, v120 offset:25672
	ds_read_u16 v69, v120 offset:25872
	ds_read_u16 v77, v120 offset:25936
	v_mfma_f32_32x32x16_bf16 v[16:31], v[122:125], v[150:153], v[16:31]
	v_perm_b32 v153, v154, v113, s14
	v_perm_b32 v152, v105, v97, s14
	v_perm_b32 v151, v89, v81, s14
	v_perm_b32 v150, v73, v65, s14
	ds_read_u16 v65, v120 offset:26136
	ds_read_u16 v73, v120 offset:26200
	ds_read_u16 v81, v120 offset:26400
	ds_read_u16 v85, v120 offset:26464
	ds_read_u16 v89, v120 offset:26664
	ds_read_u16 v93, v120 offset:26728
	ds_read_u16 v97, v120 offset:26928
	ds_read_u16 v101, v120 offset:26992
	ds_read_u16 v105, v120 offset:27192
	v_mfma_f32_32x32x16_bf16 v[0:15], v[122:125], v[150:153], v[0:15]
	v_perm_b32 v125, v169, v167, s14
	v_perm_b32 v124, v165, v163, s14
	v_perm_b32 v123, v161, v159, s14
	v_perm_b32 v122, v157, v155, s14
	ds_read_u16 v111, v120 offset:27256
	ds_read_u16 v113, v120 offset:29568
	ds_read_u16 v121, v120 offset:29632
	v_mfma_f32_32x32x16_bf16 v[16:31], v[126:129], v[122:125], v[16:31]
	v_perm_b32 v125, v170, v168, s14
	v_perm_b32 v124, v166, v164, s14
	v_perm_b32 v123, v162, v160, s14
	v_perm_b32 v122, v158, v156, s14
	s_nop 1
	v_mfma_f32_32x32x16_bf16 v[0:15], v[126:129], v[122:125], v[0:15]
	v_perm_b32 v125, v185, v183, s14
	v_perm_b32 v124, v181, v179, s14
	v_perm_b32 v123, v177, v175, s14
	v_perm_b32 v122, v173, v171, s14
	ds_read_u16 v126, v120 offset:29832
	ds_read_u16 v128, v120 offset:29896
	ds_read_u16 v127, v120 offset:30096
	v_mfma_f32_32x32x16_bf16 v[16:31], v[130:133], v[122:125], v[16:31]
	v_perm_b32 v125, v186, v184, s14
	v_perm_b32 v124, v182, v180, s14
	v_perm_b32 v123, v178, v176, s14
	v_perm_b32 v122, v174, v172, s14
	s_nop 1
	v_mfma_f32_32x32x16_bf16 v[0:15], v[130:133], v[122:125], v[0:15]
	ds_read_u16 v129, v120 offset:30160
	ds_read_u16 v130, v120 offset:30360
	ds_read_u16 v131, v120 offset:30424
	s_load_dwordx2 s[6:7], s[2:3], 0x58
	global_load_ushort v132, v[116:117], off
	v_perm_b32 v125, v201, v199, s14
	v_perm_b32 v124, v197, v195, s14
	v_perm_b32 v123, v193, v191, s14
	s_waitcnt lgkmcnt(0)
; __device__ __forceinline__ float bf2f(bf16_t b) { return __uint_as_float(((unsigned)b) << 16); }
; __device__ __forceinline__ bf16_t f2bf(float f) { return (bf16_t)(cvt_pk_bf16(f, 0.f) & 0xffffu); }
; __device__ __forceinline__ int crow(int r, int hi) { return (r & 3) + 8 * (r >> 2) + 4 * hi; }
; __device__ void gmlp_unit(const Ctx& c, int tid, int l, int ch, int g, unsigned short* T) {
;     ...
;     for (int ks = 0; ks < 8; ++ks) {
;         bf16x8 b0, b1;
; #pragma unroll
;         for (int j = 0; j < 8; ++j) { b0[j] = (short)tb[(ks * 16 + j) * 132]; b1[j] = (short)tb[(ks * 16 + j) * 132 + 32]; }
;         acc0 = __builtin_amdgcn_mfma_f32_32x32x16_bf16(af[ks], b0, acc0, 0, 0, 0);
;         acc1 = __builtin_amdgcn_mfma_f32_32x32x16_bf16(af[ks], b1, acc1, 0, 0, 0); }
; #pragma unroll
;     for (int r = 0; r < 16; ++r) { const int prow = pblk * 32 + att::crow(r, hi); const size_t t = (size_t)ch * 128 + prow;
;         const float bias = pk->in[11][(l * 8 + g) * 128 + prow];
;         bf16_t* up = AM0 + t * 1024 + g * 128 + cb0 * 32 + r32;
;         up[0] = f2bf(bf2f(up[0]) * (acc0[r] + bias)); up[32] = f2bf(bf2f(up[32]) * (acc1[r] + bias)); }
	v_lshl_add_u64 v[118:119], v[118:119], 2, s[6:7]
	global_load_dword v133, v[118:119], off
	global_load_ushort v221, v[116:117], off offset:64
	v_lshl_add_u64 v[222:223], v[114:115], 0, v[50:51]
	global_load_ushort v238, v[222:223], off offset:64
	global_load_ushort v222, v[222:223], off
	global_load_dword v223, v[118:119], off offset:4
	v_lshl_add_u64 v[224:225], v[114:115], 0, v[54:55]
	global_load_ushort v239, v[224:225], off offset:64
	global_load_ushort v224, v[224:225], off
	global_load_dword v225, v[118:119], off offset:8
	v_lshl_add_u64 v[226:227], v[114:115], 0, v[58:59]
	global_load_ushort v240, v[226:227], off offset:64
	global_load_ushort v226, v[226:227], off
	global_load_dword v227, v[118:119], off offset:12
	v_lshl_add_u64 v[228:229], v[114:115], 0, v[62:63]
	global_load_ushort v241, v[228:229], off offset:64
	global_load_ushort v228, v[228:229], off
	global_load_dword v229, v[118:119], off offset:32
	v_lshl_add_u64 v[230:231], v[114:115], 0, v[66:67]
	global_load_ushort v242, v[230:231], off offset:64
	global_load_ushort v230, v[230:231], off
	global_load_dword v231, v[118:119], off offset:36
	v_lshl_add_u64 v[232:233], v[114:115], 0, v[70:71]
	global_load_ushort v243, v[232:233], off offset:64
	global_load_ushort v232, v[232:233], off
	global_load_dword v233, v[118:119], off offset:40
	v_lshl_add_u64 v[234:235], v[114:115], 0, v[74:75]
	global_load_ushort v244, v[234:235], off offset:64
	global_load_ushort v234, v[234:235], off
	global_load_dword v235, v[118:119], off offset:44
	v_perm_b32 v122, v189, v187, s14
	s_nop 1
	v_mfma_f32_32x32x16_bf16 v[16:31], v[134:137], v[122:125], v[16:31]
	v_perm_b32 v125, v202, v200, s14
	v_perm_b32 v124, v198, v196, s14
	v_perm_b32 v123, v194, v192, s14
	v_perm_b32 v122, v190, v188, s14
	s_nop 1
	v_mfma_f32_32x32x16_bf16 v[0:15], v[134:137], v[122:125], v[0:15]
	v_perm_b32 v125, v219, v215, s14
	v_perm_b32 v124, v213, v211, s14
	v_perm_b32 v123, v209, v207, s14
	v_perm_b32 v122, v205, v203, s14
	ds_read_u16 v118, v120 offset:30624
	ds_read_u16 v134, v120 offset:30688
	ds_read_u16 v119, v120 offset:30888
	ds_read_u16 v135, v120 offset:31152
	ds_read_u16 v136, v120 offset:31416
	v_mfma_f32_32x32x16_bf16 v[16:31], v[138:141], v[122:125], v[16:31]
	v_perm_b32 v125, v220, v218, s14
	v_perm_b32 v124, v214, v212, s14
	v_perm_b32 v123, v210, v208, s14
	v_perm_b32 v122, v206, v204, s14
	s_nop 1
	v_mfma_f32_32x32x16_bf16 v[0:15], v[138:141], v[122:125], v[0:15]
	v_perm_b32 v125, v105, v97, s14
	v_perm_b32 v124, v89, v81, s14
	v_perm_b32 v123, v65, v69, s14
	v_perm_b32 v122, v57, v49, s14
	ds_read_u16 v49, v120 offset:30952
	ds_read_u16 v57, v120 offset:31216
	ds_read_u16 v65, v120 offset:31480
	s_waitcnt vmcnt(23)
	v_lshlrev_b32_e32 v69, 16, v132
	v_mfma_f32_32x32x16_bf16 v[16:31], v[142:145], v[122:125], v[16:31]
	s_waitcnt lgkmcnt(3)
	v_perm_b32 v125, v136, v135, s14
	v_perm_b32 v124, v119, v118, s14
	v_perm_b32 v123, v130, v127, s14
	v_perm_b32 v122, v126, v113, s14
	v_add_u32_e32 v118, s4, v48
	v_ashrrev_i32_e32 v119, 31, v118
	v_lshl_add_u64 v[126:127], v[114:115], 0, v[50:51]
	v_mfma_f32_32x32x16_bf16 v[16:31], v[146:149], v[122:125], v[16:31]
	v_perm_b32 v125, v111, v101, s14
	v_perm_b32 v124, v93, v85, s14
	v_perm_b32 v123, v73, v77, s14
	v_perm_b32 v122, v61, v53, s14
	v_lshl_add_u64 v[118:119], v[118:119], 2, s[6:7]
	s_waitcnt vmcnt(0)
	s_nop 5
	v_add_f32_e32 v16, v16, v133
	v_mul_f32_e32 v16, v16, v69
	v_cvt_pk_bf16_f32 v16, v16, v35
	v_mov_b32_e32 v69, v221
	v_mfma_f32_32x32x16_bf16 v[0:15], v[142:145], v[122:125], v[0:15]
	s_waitcnt lgkmcnt(0)
	v_perm_b32 v125, v65, v57, s14
	v_perm_b32 v124, v49, v134, s14
	v_perm_b32 v123, v131, v129, s14
	v_perm_b32 v122, v128, v121, s14
	global_store_short v[116:117], v16, off
	v_lshlrev_b32_e32 v16, 16, v69
	v_mfma_f32_32x32x16_bf16 v[0:15], v[146:149], v[122:125], v[0:15]
	s_nop 11
	v_add_f32_e32 v0, v0, v133
	v_mul_f32_e32 v0, v0, v16
	v_cvt_pk_bf16_f32 v0, v0, v35
	v_mov_b32_e32 v16, v222
	v_mov_b32_e32 v49, v223
	v_add_f32_e32 v1, v1, v49
	global_store_short v[116:117], v0, off offset:64
	v_lshlrev_b32_e32 v0, 16, v16
	v_add_f32_e32 v16, v17, v49
	v_mul_f32_e32 v0, v16, v0
	v_cvt_pk_bf16_f32 v0, v0, v35
	v_mov_b32_e32 v53, v238
	v_add_u32_e32 v16, s4, v52
	global_store_short v[126:127], v0, off
	v_ashrrev_i32_e32 v17, 31, v16
	v_lshl_add_u64 v[116:117], v[114:115], 0, v[54:55]
	v_lshl_add_u64 v[16:17], v[16:17], 2, s[6:7]
	v_lshlrev_b32_e32 v0, 16, v53
	v_mul_f32_e32 v0, v1, v0
	v_cvt_pk_bf16_f32 v0, v0, v35
	v_mov_b32_e32 v1, v224
	v_mov_b32_e32 v49, v225
	v_lshl_add_u64 v[16:17], v[114:115], 0, v[58:59]
	global_store_short v[126:127], v0, off offset:64
	v_lshlrev_b32_e32 v0, 16, v1
	v_add_f32_e32 v1, v18, v49
	v_mul_f32_e32 v0, v1, v0
	v_cvt_pk_bf16_f32 v18, v0, v35
	v_mov_b32_e32 v53, v239
	v_add_u32_e32 v0, s4, v56
	v_add_f32_e32 v2, v2, v49
	global_store_short v[116:117], v18, off
	v_ashrrev_i32_e32 v1, 31, v0
	v_lshl_add_u64 v[0:1], v[0:1], 2, s[6:7]
	v_lshlrev_b32_e32 v18, 16, v53
	v_mul_f32_e32 v2, v2, v18
	v_cvt_pk_bf16_f32 v2, v2, v35
	v_mov_b32_e32 v18, v226
	v_mov_b32_e32 v49, v227
	v_lshlrev_b32_e32 v0, 16, v18
	v_add_f32_e32 v1, v19, v49
	global_store_short v[116:117], v2, off offset:64
	v_mul_f32_e32 v0, v1, v0
	v_cvt_pk_bf16_f32 v2, v0, v35
	v_mov_b32_e32 v53, v240
	v_add_u32_e32 v0, s4, v60
	v_add_f32_e32 v3, v3, v49
	global_store_short v[16:17], v2, off
	v_ashrrev_i32_e32 v1, 31, v0
	v_lshl_add_u64 v[18:19], v[114:115], 0, v[62:63]
	v_lshl_add_u64 v[0:1], v[0:1], 2, s[6:7]
	v_lshlrev_b32_e32 v2, 16, v53
	v_mul_f32_e32 v2, v3, v2
	v_cvt_pk_bf16_f32 v2, v2, v35
	v_mov_b32_e32 v3, v228
	v_mov_b32_e32 v49, v229
; __device__ __forceinline__ float bf2f(bf16_t b) { return __uint_as_float(((unsigned)b) << 16); }
; __device__ __forceinline__ bf16_t f2bf(float f) { return (bf16_t)(cvt_pk_bf16(f, 0.f) & 0xffffu); }
; __device__ __forceinline__ int crow(int r, int hi) { return (r & 3) + 8 * (r >> 2) + 4 * hi; }
; __device__ void gmlp_unit(const Ctx& c, int tid, int l, int ch, int g, unsigned short* T) {
;     ...
;     for (int r = 0; r < 16; ++r) { const int prow = pblk * 32 + att::crow(r, hi); const size_t t = (size_t)ch * 128 + prow;
;         const float bias = pk->in[11][(l * 8 + g) * 128 + prow];
;         bf16_t* up = AM0 + t * 1024 + g * 128 + cb0 * 32 + r32;
;         up[0] = f2bf(bf2f(up[0]) * (acc0[r] + bias)); up[32] = f2bf(bf2f(up[32]) * (acc1[r] + bias)); }
	v_lshlrev_b32_e32 v0, 16, v3
	v_add_f32_e32 v1, v20, v49
	global_store_short v[16:17], v2, off offset:64
	v_mul_f32_e32 v0, v1, v0
	v_cvt_pk_bf16_f32 v16, v0, v35
	v_mov_b32_e32 v17, v241
	v_add_u32_e32 v0, s4, v64
	v_add_f32_e32 v4, v4, v49
	global_store_short v[18:19], v16, off
	v_ashrrev_i32_e32 v1, 31, v0
	v_lshl_add_u64 v[2:3], v[114:115], 0, v[66:67]
	v_lshl_add_u64 v[0:1], v[0:1], 2, s[6:7]
	v_lshlrev_b32_e32 v16, 16, v17
	v_mul_f32_e32 v4, v4, v16
	v_cvt_pk_bf16_f32 v4, v4, v35
	v_mov_b32_e32 v16, v230
	v_mov_b32_e32 v20, v231
	v_lshlrev_b32_e32 v0, 16, v16
	v_add_f32_e32 v1, v21, v20
	global_store_short v[18:19], v4, off offset:64
	v_mul_f32_e32 v0, v1, v0
	v_cvt_pk_bf16_f32 v4, v0, v35
	v_mov_b32_e32 v18, v242
	v_add_u32_e32 v0, s4, v68
	v_add_f32_e32 v5, v5, v20
	global_store_short v[2:3], v4, off
	v_ashrrev_i32_e32 v1, 31, v0
	v_lshl_add_u64 v[16:17], v[114:115], 0, v[70:71]
	v_lshl_add_u64 v[0:1], v[0:1], 2, s[6:7]
	v_lshlrev_b32_e32 v4, 16, v18
	v_mul_f32_e32 v4, v5, v4
	v_cvt_pk_bf16_f32 v4, v4, v35
	v_mov_b32_e32 v5, v232
	v_mov_b32_e32 v18, v233
	v_lshlrev_b32_e32 v0, 16, v5
	v_add_f32_e32 v1, v22, v18
	global_store_short v[2:3], v4, off offset:64
	v_mul_f32_e32 v0, v1, v0
	v_cvt_pk_bf16_f32 v4, v0, v35
	v_mov_b32_e32 v5, v243
	v_add_u32_e32 v0, s4, v72
	v_add_f32_e32 v6, v6, v18
	global_store_short v[16:17], v4, off
	v_ashrrev_i32_e32 v1, 31, v0
	v_lshl_add_u64 v[2:3], v[114:115], 0, v[74:75]
	v_lshl_add_u64 v[0:1], v[0:1], 2, s[6:7]
	v_lshlrev_b32_e32 v4, 16, v5
	v_mul_f32_e32 v4, v6, v4
	v_cvt_pk_bf16_f32 v4, v4, v35
	v_mov_b32_e32 v5, v234
	v_mov_b32_e32 v6, v235
	v_lshlrev_b32_e32 v0, 16, v5
	v_add_f32_e32 v1, v23, v6
	global_store_short v[16:17], v4, off offset:64
	v_mul_f32_e32 v0, v1, v0
	v_cvt_pk_bf16_f32 v16, v0, v35
	v_mov_b32_e32 v17, v244
	v_add_u32_e32 v0, s4, v76
	v_add_f32_e32 v6, v7, v6
	v_ashrrev_i32_e32 v1, 31, v0
	v_lshl_add_u64 v[4:5], v[114:115], 0, v[78:79]
	v_lshl_add_u64 v[0:1], v[0:1], 2, s[6:7]
	global_store_short v[2:3], v16, off
	v_lshlrev_b32_e32 v7, 16, v17
	v_mul_f32_e32 v6, v6, v7
	v_cvt_pk_bf16_f32 v6, v6, v35
	v_lshl_add_u64 v[222:223], v[114:115], 0, v[78:79]
	global_load_ushort v221, v[222:223], off offset:64
	global_load_ushort v222, v[222:223], off
	global_load_dword v223, v[0:1], off offset:0
	v_lshl_add_u64 v[224:225], v[114:115], 0, v[82:83]
	global_load_ushort v238, v[224:225], off offset:64
	global_load_ushort v224, v[224:225], off
	global_load_dword v225, v[0:1], off offset:4
	v_lshl_add_u64 v[226:227], v[114:115], 0, v[86:87]
	global_load_ushort v239, v[226:227], off offset:64
	global_load_ushort v226, v[226:227], off
	global_load_dword v227, v[0:1], off offset:8
	v_lshl_add_u64 v[228:229], v[114:115], 0, v[90:91]
	global_load_ushort v240, v[228:229], off offset:64
	global_load_ushort v228, v[228:229], off
	global_load_dword v229, v[0:1], off offset:12
	v_lshl_add_u64 v[230:231], v[114:115], 0, v[94:95]
	global_load_ushort v241, v[230:231], off offset:64
	global_load_ushort v230, v[230:231], off
	global_load_dword v231, v[0:1], off offset:32
	v_lshl_add_u64 v[232:233], v[114:115], 0, v[98:99]
	global_load_ushort v242, v[232:233], off offset:64
	global_load_ushort v232, v[232:233], off
	global_load_dword v233, v[0:1], off offset:36
	v_lshl_add_u64 v[234:235], v[114:115], 0, v[102:103]
	global_load_ushort v243, v[234:235], off offset:64
	global_load_ushort v234, v[234:235], off
	global_load_dword v235, v[0:1], off offset:40
	v_lshl_add_u64 v[236:237], v[114:115], 0, v[106:107]
	global_load_ushort v244, v[236:237], off offset:64
	global_load_ushort v236, v[236:237], off
	global_load_dword v237, v[0:1], off offset:44
	s_waitcnt vmcnt(0)
; __device__ __forceinline__ float bf2f(bf16_t b) { return __uint_as_float(((unsigned)b) << 16); }
; __device__ __forceinline__ bf16_t f2bf(float f) { return (bf16_t)(cvt_pk_bf16(f, 0.f) & 0xffffu); }
; __device__ __forceinline__ int crow(int r, int hi) { return (r & 3) + 8 * (r >> 2) + 4 * hi; }
; __device__ void gmlp_unit(const Ctx& c, int tid, int l, int ch, int g, unsigned short* T) {
;     ...
;     for (int r = 0; r < 16; ++r) { const int prow = pblk * 32 + att::crow(r, hi); const size_t t = (size_t)ch * 128 + prow;
;         const float bias = pk->in[11][(l * 8 + g) * 128 + prow];
;         bf16_t* up = AM0 + t * 1024 + g * 128 + cb0 * 32 + r32;
;         up[0] = f2bf(bf2f(up[0]) * (acc0[r] + bias)); up[32] = f2bf(bf2f(up[32]) * (acc1[r] + bias)); }
	v_mov_b32_e32 v7, v222
	v_mov_b32_e32 v16, v223
	v_lshlrev_b32_e32 v0, 16, v7
	v_add_f32_e32 v1, v24, v16
	global_store_short v[2:3], v6, off offset:64
	v_mul_f32_e32 v0, v1, v0
	v_cvt_pk_bf16_f32 v6, v0, v35
	v_mov_b32_e32 v7, v221
	v_add_u32_e32 v0, s4, v80
	v_add_f32_e32 v8, v8, v16
	global_store_short v[4:5], v6, off
	v_ashrrev_i32_e32 v1, 31, v0
	v_lshl_add_u64 v[2:3], v[114:115], 0, v[82:83]
	v_lshl_add_u64 v[0:1], v[0:1], 2, s[6:7]
	v_lshlrev_b32_e32 v6, 16, v7
	v_mul_f32_e32 v6, v8, v6
	v_cvt_pk_bf16_f32 v6, v6, v35
	v_mov_b32_e32 v7, v224
	v_mov_b32_e32 v8, v225
	v_lshlrev_b32_e32 v0, 16, v7
	v_add_f32_e32 v1, v25, v8
	global_store_short v[4:5], v6, off offset:64
	v_mul_f32_e32 v0, v1, v0
	v_cvt_pk_bf16_f32 v6, v0, v35
	v_mov_b32_e32 v7, v238
	v_add_u32_e32 v0, s4, v84
	v_add_f32_e32 v8, v9, v8
	global_store_short v[2:3], v6, off
	v_ashrrev_i32_e32 v1, 31, v0
	v_lshl_add_u64 v[4:5], v[114:115], 0, v[86:87]
	v_lshl_add_u64 v[0:1], v[0:1], 2, s[6:7]
	v_lshlrev_b32_e32 v6, 16, v7
	v_mul_f32_e32 v6, v8, v6
	v_cvt_pk_bf16_f32 v6, v6, v35
	v_mov_b32_e32 v7, v226
	v_mov_b32_e32 v8, v227
	v_lshlrev_b32_e32 v0, 16, v7
	v_add_f32_e32 v1, v26, v8
	global_store_short v[2:3], v6, off offset:64
	v_mul_f32_e32 v0, v1, v0
	v_cvt_pk_bf16_f32 v6, v0, v35
	v_mov_b32_e32 v7, v239
	v_add_u32_e32 v0, s4, v88
	v_add_f32_e32 v8, v10, v8
	global_store_short v[4:5], v6, off
	v_ashrrev_i32_e32 v1, 31, v0
	v_lshl_add_u64 v[2:3], v[114:115], 0, v[90:91]
	v_lshl_add_u64 v[0:1], v[0:1], 2, s[6:7]
	v_lshlrev_b32_e32 v6, 16, v7
	v_mul_f32_e32 v6, v8, v6
	v_cvt_pk_bf16_f32 v6, v6, v35
	v_mov_b32_e32 v7, v228
	v_mov_b32_e32 v8, v229
	v_lshlrev_b32_e32 v0, 16, v7
	v_add_f32_e32 v1, v27, v8
	global_store_short v[4:5], v6, off offset:64
	v_mul_f32_e32 v0, v1, v0
	v_cvt_pk_bf16_f32 v6, v0, v35
	v_mov_b32_e32 v7, v240
	v_add_u32_e32 v0, s4, v92
	v_add_f32_e32 v8, v11, v8
	global_store_short v[2:3], v6, off
	v_ashrrev_i32_e32 v1, 31, v0
	v_lshl_add_u64 v[4:5], v[114:115], 0, v[94:95]
	v_lshl_add_u64 v[0:1], v[0:1], 2, s[6:7]
	v_lshlrev_b32_e32 v6, 16, v7
	v_mul_f32_e32 v6, v8, v6
	v_cvt_pk_bf16_f32 v6, v6, v35
	v_mov_b32_e32 v7, v230
	v_mov_b32_e32 v8, v231
	v_lshlrev_b32_e32 v0, 16, v7
	v_add_f32_e32 v1, v28, v8
	global_store_short v[2:3], v6, off offset:64
	v_mul_f32_e32 v0, v1, v0
	v_cvt_pk_bf16_f32 v6, v0, v35
	v_mov_b32_e32 v7, v241
	v_add_u32_e32 v0, s4, v96
	v_add_f32_e32 v8, v12, v8
	global_store_short v[4:5], v6, off
	v_ashrrev_i32_e32 v1, 31, v0
	v_lshl_add_u64 v[2:3], v[114:115], 0, v[98:99]
	v_lshl_add_u64 v[0:1], v[0:1], 2, s[6:7]
	v_lshlrev_b32_e32 v6, 16, v7
	v_mul_f32_e32 v6, v8, v6
	v_cvt_pk_bf16_f32 v6, v6, v35
	v_mov_b32_e32 v7, v232
	v_mov_b32_e32 v8, v233
	v_lshlrev_b32_e32 v0, 16, v7
	v_add_f32_e32 v1, v29, v8
	global_store_short v[4:5], v6, off offset:64
	v_mul_f32_e32 v0, v1, v0
	v_cvt_pk_bf16_f32 v6, v0, v35
	v_mov_b32_e32 v7, v242
	v_add_u32_e32 v0, s4, v100
	v_add_f32_e32 v8, v13, v8
	global_store_short v[2:3], v6, off
	v_ashrrev_i32_e32 v1, 31, v0
	v_lshl_add_u64 v[4:5], v[114:115], 0, v[102:103]
	v_lshl_add_u64 v[0:1], v[0:1], 2, s[6:7]
	v_lshlrev_b32_e32 v6, 16, v7
	v_mul_f32_e32 v6, v8, v6
	v_cvt_pk_bf16_f32 v6, v6, v35
	v_mov_b32_e32 v7, v234
	v_mov_b32_e32 v8, v235
	v_lshlrev_b32_e32 v0, 16, v7
	v_add_f32_e32 v1, v30, v8
	global_store_short v[2:3], v6, off offset:64
	v_mul_f32_e32 v0, v1, v0
	v_cvt_pk_bf16_f32 v6, v0, v35
	v_mov_b32_e32 v7, v243
	v_add_u32_e32 v0, s4, v104
	v_add_f32_e32 v8, v14, v8
	global_store_short v[4:5], v6, off
	v_ashrrev_i32_e32 v1, 31, v0
	v_lshl_add_u64 v[2:3], v[114:115], 0, v[106:107]
	v_lshl_add_u64 v[0:1], v[0:1], 2, s[6:7]
	v_lshlrev_b32_e32 v6, 16, v7
	v_mul_f32_e32 v6, v8, v6
	v_cvt_pk_bf16_f32 v6, v6, v35
	v_mov_b32_e32 v7, v236
	v_mov_b32_e32 v8, v237
	v_lshlrev_b32_e32 v0, 16, v7
	v_add_f32_e32 v1, v31, v8
	v_mul_f32_e32 v0, v1, v0
	global_store_short v[4:5], v6, off offset:64
	v_cvt_pk_bf16_f32 v0, v0, v35
	v_mov_b32_e32 v1, v244
	v_add_f32_e32 v4, v15, v8
	global_store_short v[2:3], v0, off
	v_lshlrev_b32_e32 v0, 16, v1
	v_mul_f32_e32 v0, v4, v0
	v_cvt_pk_bf16_f32 v0, v0, v35
	global_store_short v[2:3], v0, off offset:64
	s_barrier
	s_cbranch_scc1 .LBB0_1544
